# strategy 7.5 packed-to-scalar: softmax row-sum trees in the layer 0/3 attention pair loops use scalar v_add_f32 chains instead of 15 v_pk_add_f32
# speedup vs baseline: 1.0068x; 1.0018x over previous
; __device__ __forceinline__ unsigned cvtpk(float lo, float hi) { typedef __bf16 b2 __attribute__((ext_vector_type(2))); f32x2 v = {lo, hi}; b2 b = __builtin_convertvector(v, b2); return __builtin_bit_cast(unsigned, b); }
; __device__ __forceinline__ int crow(int r, int hi) { return (r & 3) + 8 * (r >> 2) + 4 * hi; }
; #define ATT_VREAD(dst, q_) do { const LAS char* vp_ = (const LAS char*)vb + (((q_) >> 1) * 32 + 16 * ((q_) & 1)) * VSTR; \
;         _Pragma("unroll") for (int d_ = 0; d_ < 4; ++d_) { dst[d_][0] = vtr(vp_ + voff[d_][0]); dst[d_][1] = vtr(vp_ + 8 * VSTR + voff[d_][1]); } } while (0)
;     ...
;         float rsa[4] = {0.f, 0.f, 0.f, 0.f};
; #pragma unroll
;         for (int r = 0; r < 16; ++r) { float p0 = __builtin_amdgcn_exp2f(s0[r] - mrun), p1 = __builtin_amdgcn_exp2f(s1[r] - mrun);
;             if (LAYER == 1) { const int kv = crow(r, hi); p0 = ((w0 >> kv) & 1u) ? p0 : 0.f; p1 = ((w1 >> kv) & 1u) ? p1 : 0.f; }
;             s0[r] = p0; s1[r] = p1; rsa[r & 3] += p0 + p1; }
;         lrun += (rsa[0] + rsa[1]) + (rsa[2] + rsa[3]);
; #pragma unroll
;         for (int s = 0; s < 2; ++s) {
;             v4u x; x.x = cvtpk(s0[8 * s + 0], s0[8 * s + 1]); x.y = cvtpk(s0[8 * s + 2], s0[8 * s + 3]); x.z = cvtpk(s0[8 * s + 4], s0[8 * s + 5]); x.w = cvtpk(s0[8 * s + 6], s0[8 * s + 7]); pb[0][s] = __builtin_bit_cast(bf16x8, x);
;             v4u y; y.x = cvtpk(s1[8 * s + 0], s1[8 * s + 1]); y.y = cvtpk(s1[8 * s + 2], s1[8 * s + 3]); y.z = cvtpk(s1[8 * s + 4], s1[8 * s + 5]); y.w = cvtpk(s1[8 * s + 6], s1[8 * s + 7]); pb[1][s] = __builtin_bit_cast(bf16x8, y); }
;     };
;     ...
;             if (wka) { vb = sa + KBUF + vlane; ATT_VREAD(vpre, 0); SM(wa0, wa1, a0, a1, pba);
;                 ATT_VREAD(va, 1); __builtin_amdgcn_s_setprio(1); ATT_PV(vpre, pba, 0); __builtin_amdgcn_s_setprio(0);
;                 ATT_VREAD(vbb, 2); __builtin_amdgcn_s_setprio(1); ATT_PV(va, pba, 1); __builtin_amdgcn_s_setprio(0);
;                 ATT_VREAD(va, 3); __builtin_amdgcn_s_setprio(1); ATT_PV(vbb, pba, 2); __builtin_amdgcn_s_setprio(0);
;                 __builtin_amdgcn_s_setprio(1); ATT_PV(va, pba, 3); __builtin_amdgcn_s_setprio(0); }
.LBB0_589:
	v_sub_f32_e32 v68, v68, v170
	v_sub_f32_e32 v100, v100, v170
	v_sub_f32_e32 v70, v70, v170
	v_sub_f32_e32 v102, v102, v170
	v_exp_f32_e32 v68, v68
	v_exp_f32_e32 v100, v100
	v_sub_f32_e32 v69, v69, v170
	v_sub_f32_e32 v101, v101, v170
	v_exp_f32_e32 v70, v70
	v_exp_f32_e32 v102, v102
	v_sub_f32_e32 v71, v71, v170
	v_sub_f32_e32 v103, v103, v170
	v_exp_f32_e32 v69, v69
	v_exp_f32_e32 v101, v101
	v_exp_f32_e32 v71, v71
	v_exp_f32_e32 v103, v103
	v_sub_f32_e32 v72, v72, v170
	v_sub_f32_e32 v104, v104, v170
	v_sub_f32_e32 v74, v74, v170
	v_sub_f32_e32 v106, v106, v170
	v_exp_f32_e32 v72, v72
	v_exp_f32_e32 v104, v104
	v_exp_f32_e32 v74, v74
	v_exp_f32_e32 v106, v106
	v_sub_f32_e32 v73, v73, v170
	v_sub_f32_e32 v105, v105, v170
	v_sub_f32_e32 v75, v75, v170
	v_sub_f32_e32 v107, v107, v170
	v_exp_f32_e32 v73, v73
	v_exp_f32_e32 v105, v105
	v_exp_f32_e32 v75, v75
	v_exp_f32_e32 v107, v107
	v_sub_f32_e32 v76, v76, v170
	v_sub_f32_e32 v108, v108, v170
	v_sub_f32_e32 v78, v78, v170
	v_sub_f32_e32 v110, v110, v170
	v_exp_f32_e32 v76, v76
	v_exp_f32_e32 v108, v108
	v_exp_f32_e32 v78, v78
	v_exp_f32_e32 v110, v110
	v_sub_f32_e32 v77, v77, v170
	v_sub_f32_e32 v109, v109, v170
	v_sub_f32_e32 v79, v79, v170
	v_sub_f32_e32 v111, v111, v170
	v_exp_f32_e32 v77, v77
	v_exp_f32_e32 v109, v109
	v_exp_f32_e32 v79, v79
	v_exp_f32_e32 v111, v111
	v_sub_f32_e32 v80, v80, v170
	v_sub_f32_e32 v112, v112, v170
	v_sub_f32_e32 v82, v82, v170
	v_sub_f32_e32 v114, v114, v170
	ds_read_b64_tr_b16 v[220:221], v200 offset:20480
	ds_read_b64_tr_b16 v[222:223], v201 offset:22528
	ds_read_b64_tr_b16 v[224:225], v202 offset:20480
	ds_read_b64_tr_b16 v[226:227], v203 offset:22528
	ds_read_b64_tr_b16 v[228:229], v204 offset:20480
	ds_read_b64_tr_b16 v[230:231], v205 offset:22528
	ds_read_b64_tr_b16 v[232:233], v206 offset:20480
	ds_read_b64_tr_b16 v[234:235], v207 offset:22528
	v_exp_f32_e32 v80, v80
	v_exp_f32_e32 v112, v112
	v_exp_f32_e32 v82, v82
	v_exp_f32_e32 v114, v114
	v_sub_f32_e32 v81, v81, v170
	v_sub_f32_e32 v113, v113, v170
	v_sub_f32_e32 v83, v83, v170
	v_sub_f32_e32 v115, v115, v170
	v_exp_f32_e32 v81, v81
	v_exp_f32_e32 v113, v113
	v_exp_f32_e32 v83, v83
	v_exp_f32_e32 v115, v115
	s_nop 0
	v_add_f32_e32 v208, v68, v76
	v_add_f32_e32 v209, v69, v77
	v_add_f32_e32 v210, v70, v78
	v_add_f32_e32 v211, v71, v79
	v_add_f32_e32 v212, v72, v80
	v_add_f32_e32 v213, v73, v81
	v_add_f32_e32 v214, v74, v82
	v_add_f32_e32 v215, v75, v83
	v_add_f32_e32 v208, v208, v100
	v_add_f32_e32 v209, v209, v101
	v_add_f32_e32 v210, v210, v102
	v_add_f32_e32 v211, v211, v103
	v_add_f32_e32 v212, v212, v104
	v_add_f32_e32 v213, v213, v105
	v_add_f32_e32 v214, v214, v106
	v_add_f32_e32 v215, v215, v107
	v_add_f32_e32 v208, v208, v108
	v_add_f32_e32 v209, v209, v109
	v_add_f32_e32 v210, v210, v110
	v_add_f32_e32 v211, v211, v111
	v_add_f32_e32 v212, v212, v112
	v_add_f32_e32 v213, v213, v113
	v_add_f32_e32 v214, v214, v114
	v_add_f32_e32 v215, v215, v115
	v_add_f32_e32 v208, v208, v212
	v_add_f32_e32 v209, v209, v213
	v_add_f32_e32 v210, v210, v214
	v_add_f32_e32 v211, v211, v215
	v_add_f32_e32 v208, v208, v210
	v_add_f32_e32 v209, v209, v211
	v_add_f32_e32 v240, v208, v209
	v_cvt_pk_bf16_f32 v214, v104, v105
	v_cvt_pk_bf16_f32 v212, v100, v101
	v_cvt_pk_bf16_f32 v210, v72, v73
	v_cvt_pk_bf16_f32 v208, v68, v69
	v_cvt_pk_bf16_f32 v209, v70, v71
	v_cvt_pk_bf16_f32 v211, v74, v75
	v_cvt_pk_bf16_f32 v213, v102, v103
	v_cvt_pk_bf16_f32 v215, v106, v107
	v_cvt_pk_bf16_f32 v216, v76, v77
	v_cvt_pk_bf16_f32 v217, v78, v79
	v_cvt_pk_bf16_f32 v218, v80, v81
	v_cvt_pk_bf16_f32 v219, v82, v83
	v_cvt_pk_bf16_f32 v236, v108, v109
	v_cvt_pk_bf16_f32 v237, v110, v111
	v_cvt_pk_bf16_f32 v238, v112, v113
	v_cvt_pk_bf16_f32 v239, v114, v115
	s_nop 0
	s_waitcnt lgkmcnt(8)
	v_mfma_f32_32x32x16_bf16 v[52:67], v[152:155], v[208:211], v[52:67]
	v_add_f32_e32 v167, v167, v240
	v_mfma_f32_32x32x16_bf16 v[36:51], v[148:151], v[208:211], v[36:51]
	v_mfma_f32_32x32x16_bf16 v[20:35], v[160:163], v[208:211], v[20:35]
	v_mfma_f32_32x32x16_bf16 v[4:19], v[156:159], v[208:211], v[4:19]
	s_nop 0
	ds_read_b64_tr_b16 v[148:149], v200 offset:24576
	ds_read_b64_tr_b16 v[150:151], v201 offset:26624
	ds_read_b64_tr_b16 v[152:153], v202 offset:24576
	ds_read_b64_tr_b16 v[154:155], v203 offset:26624
	ds_read_b64_tr_b16 v[156:157], v204 offset:24576
	ds_read_b64_tr_b16 v[158:159], v205 offset:26624
	ds_read_b64_tr_b16 v[160:161], v206 offset:24576
	ds_read_b64_tr_b16 v[162:163], v207 offset:26624
	s_nop 0
	s_waitcnt lgkmcnt(14)
	v_mfma_f32_32x32x16_bf16 v[52:67], v[220:223], v[216:219], v[52:67]
	s_waitcnt lgkmcnt(12)
	v_mfma_f32_32x32x16_bf16 v[36:51], v[224:227], v[216:219], v[36:51]
	s_waitcnt lgkmcnt(10)
	v_mfma_f32_32x32x16_bf16 v[20:35], v[228:231], v[216:219], v[20:35]
	s_waitcnt lgkmcnt(8)
	v_mfma_f32_32x32x16_bf16 v[4:19], v[232:235], v[216:219], v[4:19]
	s_nop 0
	ds_read_b64_tr_b16 v[208:209], v200 offset:28672
	ds_read_b64_tr_b16 v[210:211], v201 offset:30720
	ds_read_b64_tr_b16 v[216:217], v202 offset:28672
	ds_read_b64_tr_b16 v[218:219], v203 offset:30720
	ds_read_b64_tr_b16 v[220:221], v204 offset:28672
	ds_read_b64_tr_b16 v[222:223], v205 offset:30720
	ds_read_b64_tr_b16 v[224:225], v206 offset:28672
	ds_read_b64_tr_b16 v[226:227], v207 offset:30720
	s_nop 0
	s_waitcnt lgkmcnt(14)
	v_mfma_f32_32x32x16_bf16 v[52:67], v[148:151], v[212:215], v[52:67]
	s_waitcnt lgkmcnt(12)
	v_mfma_f32_32x32x16_bf16 v[36:51], v[152:155], v[212:215], v[36:51]
	s_waitcnt lgkmcnt(10)
	v_mfma_f32_32x32x16_bf16 v[20:35], v[156:159], v[212:215], v[20:35]
	s_waitcnt lgkmcnt(8)
	v_mfma_f32_32x32x16_bf16 v[4:19], v[160:163], v[212:215], v[4:19]
	s_nop 0
	s_nop 0
	s_waitcnt lgkmcnt(6)
	v_mfma_f32_32x32x16_bf16 v[52:67], v[208:211], v[236:239], v[52:67]
	s_waitcnt lgkmcnt(4)
	v_mfma_f32_32x32x16_bf16 v[36:51], v[216:219], v[236:239], v[36:51]
	s_waitcnt lgkmcnt(2)
	v_mfma_f32_32x32x16_bf16 v[20:35], v[220:223], v[236:239], v[20:35]
	s_waitcnt lgkmcnt(0)
	v_mfma_f32_32x32x16_bf16 v[4:19], v[224:227], v[236:239], v[4:19]
	s_nop 0

; __device__ __forceinline__ unsigned cvtpk(float lo, float hi) { typedef __bf16 b2 __attribute__((ext_vector_type(2))); f32x2 v = {lo, hi}; b2 b = __builtin_convertvector(v, b2); return __builtin_bit_cast(unsigned, b); }
; __device__ __forceinline__ int crow(int r, int hi) { return (r & 3) + 8 * (r >> 2) + 4 * hi; }
; #define ATT_VREAD(dst, q_) do { const LAS char* vp_ = (const LAS char*)vb + (((q_) >> 1) * 32 + 16 * ((q_) & 1)) * VSTR; \
;         _Pragma("unroll") for (int d_ = 0; d_ < 4; ++d_) { dst[d_][0] = vtr(vp_ + voff[d_][0]); dst[d_][1] = vtr(vp_ + 8 * VSTR + voff[d_][1]); } } while (0)
;     ...
;         for (int r = 0; r < 16; ++r) { float p0 = __builtin_amdgcn_exp2f(s0[r] - mrun), p1 = __builtin_amdgcn_exp2f(s1[r] - mrun);
;             if (LAYER == 1) { const int kv = crow(r, hi); p0 = ((w0 >> kv) & 1u) ? p0 : 0.f; p1 = ((w1 >> kv) & 1u) ? p1 : 0.f; }
;             s0[r] = p0; s1[r] = p1; rsa[r & 3] += p0 + p1; }
;         lrun += (rsa[0] + rsa[1]) + (rsa[2] + rsa[3]);
; #pragma unroll
;         for (int s = 0; s < 2; ++s) {
;             v4u x; x.x = cvtpk(s0[8 * s + 0], s0[8 * s + 1]); x.y = cvtpk(s0[8 * s + 2], s0[8 * s + 3]); x.z = cvtpk(s0[8 * s + 4], s0[8 * s + 5]); x.w = cvtpk(s0[8 * s + 6], s0[8 * s + 7]); pb[0][s] = __builtin_bit_cast(bf16x8, x);
;             v4u y; y.x = cvtpk(s1[8 * s + 0], s1[8 * s + 1]); y.y = cvtpk(s1[8 * s + 2], s1[8 * s + 3]); y.z = cvtpk(s1[8 * s + 4], s1[8 * s + 5]); y.w = cvtpk(s1[8 * s + 6], s1[8 * s + 7]); pb[1][s] = __builtin_bit_cast(bf16x8, y); }
;     ...
;             if (wka) { vb = sa + KBUF + vlane; ATT_VREAD(vpre, 0); SM(wa0, wa1, a0, a1, pba);
;                 ATT_VREAD(va, 1); __builtin_amdgcn_s_setprio(1); ATT_PV(vpre, pba, 0); __builtin_amdgcn_s_setprio(0);
;                 ATT_VREAD(vbb, 2); __builtin_amdgcn_s_setprio(1); ATT_PV(va, pba, 1); __builtin_amdgcn_s_setprio(0);
;                 ATT_VREAD(va, 3); __builtin_amdgcn_s_setprio(1); ATT_PV(vbb, pba, 2); __builtin_amdgcn_s_setprio(0);
;                 __builtin_amdgcn_s_setprio(1); ATT_PV(va, pba, 3); __builtin_amdgcn_s_setprio(0); }
.LBB0_593:
	v_sub_f32_e32 v84, v84, v170
	v_sub_f32_e32 v116, v116, v170
	v_sub_f32_e32 v86, v86, v170
	v_sub_f32_e32 v118, v118, v170
	v_exp_f32_e32 v84, v84
	v_exp_f32_e32 v116, v116
	v_sub_f32_e32 v85, v85, v170
	v_sub_f32_e32 v117, v117, v170
	v_exp_f32_e32 v86, v86
	v_exp_f32_e32 v118, v118
	v_sub_f32_e32 v87, v87, v170
	v_sub_f32_e32 v119, v119, v170
	v_exp_f32_e32 v85, v85
	v_exp_f32_e32 v117, v117
	v_exp_f32_e32 v87, v87
	v_exp_f32_e32 v119, v119
	v_sub_f32_e32 v88, v88, v170
	v_sub_f32_e32 v120, v120, v170
	v_sub_f32_e32 v90, v90, v170
	v_sub_f32_e32 v122, v122, v170
	v_exp_f32_e32 v88, v88
	v_exp_f32_e32 v120, v120
	v_exp_f32_e32 v90, v90
	v_exp_f32_e32 v122, v122
	v_sub_f32_e32 v89, v89, v170
	v_sub_f32_e32 v121, v121, v170
	v_sub_f32_e32 v91, v91, v170
	v_sub_f32_e32 v123, v123, v170
	v_exp_f32_e32 v89, v89
	v_exp_f32_e32 v121, v121
	v_exp_f32_e32 v91, v91
	v_exp_f32_e32 v123, v123
	v_sub_f32_e32 v92, v92, v170
	v_sub_f32_e32 v124, v124, v170
	v_sub_f32_e32 v94, v94, v170
	v_sub_f32_e32 v126, v126, v170
	v_exp_f32_e32 v92, v92
	v_exp_f32_e32 v124, v124
	v_exp_f32_e32 v94, v94
	v_exp_f32_e32 v126, v126
	v_sub_f32_e32 v93, v93, v170
	v_sub_f32_e32 v125, v125, v170
	v_sub_f32_e32 v95, v95, v170
	v_sub_f32_e32 v127, v127, v170
	v_exp_f32_e32 v93, v93
	v_exp_f32_e32 v125, v125
	v_exp_f32_e32 v95, v95
	v_exp_f32_e32 v127, v127
	v_sub_f32_e32 v96, v96, v170
	v_sub_f32_e32 v128, v128, v170
	v_sub_f32_e32 v98, v98, v170
	v_sub_f32_e32 v130, v130, v170
	ds_read_b64_tr_b16 v[220:221], v200 offset:53248
	ds_read_b64_tr_b16 v[222:223], v201 offset:55296
	ds_read_b64_tr_b16 v[224:225], v202 offset:53248
	ds_read_b64_tr_b16 v[226:227], v203 offset:55296
	ds_read_b64_tr_b16 v[228:229], v204 offset:53248
	ds_read_b64_tr_b16 v[230:231], v205 offset:55296
	ds_read_b64_tr_b16 v[232:233], v206 offset:53248
	ds_read_b64_tr_b16 v[234:235], v207 offset:55296
	v_exp_f32_e32 v96, v96
	v_exp_f32_e32 v128, v128
	v_exp_f32_e32 v98, v98
	v_exp_f32_e32 v130, v130
	v_sub_f32_e32 v97, v97, v170
	v_sub_f32_e32 v129, v129, v170
	v_sub_f32_e32 v99, v99, v170
	v_sub_f32_e32 v131, v131, v170
	v_exp_f32_e32 v97, v97
	v_exp_f32_e32 v129, v129
	v_exp_f32_e32 v99, v99
	v_exp_f32_e32 v131, v131
	s_nop 0
	v_add_f32_e32 v208, v84, v92
	v_add_f32_e32 v209, v85, v93
	v_add_f32_e32 v210, v86, v94
	v_add_f32_e32 v211, v87, v95
	v_add_f32_e32 v212, v88, v96
	v_add_f32_e32 v213, v89, v97
	v_add_f32_e32 v214, v90, v98
	v_add_f32_e32 v215, v91, v99
	v_add_f32_e32 v208, v208, v116
	v_add_f32_e32 v209, v209, v117
	v_add_f32_e32 v210, v210, v118
	v_add_f32_e32 v211, v211, v119
	v_add_f32_e32 v212, v212, v120
	v_add_f32_e32 v213, v213, v121
	v_add_f32_e32 v214, v214, v122
	v_add_f32_e32 v215, v215, v123
	v_add_f32_e32 v208, v208, v124
	v_add_f32_e32 v209, v209, v125
	v_add_f32_e32 v210, v210, v126
	v_add_f32_e32 v211, v211, v127
	v_add_f32_e32 v212, v212, v128
	v_add_f32_e32 v213, v213, v129
	v_add_f32_e32 v214, v214, v130
	v_add_f32_e32 v215, v215, v131
	v_add_f32_e32 v208, v208, v212
	v_add_f32_e32 v209, v209, v213
	v_add_f32_e32 v210, v210, v214
	v_add_f32_e32 v211, v211, v215
	v_add_f32_e32 v208, v208, v210
	v_add_f32_e32 v209, v209, v211
	v_add_f32_e32 v240, v208, v209
	v_cvt_pk_bf16_f32 v214, v120, v121
	v_cvt_pk_bf16_f32 v212, v116, v117
	v_cvt_pk_bf16_f32 v210, v88, v89
	v_cvt_pk_bf16_f32 v208, v84, v85
	v_cvt_pk_bf16_f32 v209, v86, v87
	v_cvt_pk_bf16_f32 v211, v90, v91
	v_cvt_pk_bf16_f32 v213, v118, v119
	v_cvt_pk_bf16_f32 v215, v122, v123
	v_cvt_pk_bf16_f32 v216, v92, v93
	v_cvt_pk_bf16_f32 v217, v94, v95
	v_cvt_pk_bf16_f32 v218, v96, v97
	v_cvt_pk_bf16_f32 v219, v98, v99
	v_cvt_pk_bf16_f32 v236, v124, v125
	v_cvt_pk_bf16_f32 v237, v126, v127
	v_cvt_pk_bf16_f32 v238, v128, v129
	v_cvt_pk_bf16_f32 v239, v130, v131
	s_nop 0
	s_waitcnt lgkmcnt(8)
	v_mfma_f32_32x32x16_bf16 v[52:67], v[152:155], v[208:211], v[52:67]
	v_add_f32_e32 v167, v167, v240
	v_mfma_f32_32x32x16_bf16 v[36:51], v[148:151], v[208:211], v[36:51]
	v_mfma_f32_32x32x16_bf16 v[20:35], v[160:163], v[208:211], v[20:35]
	v_mfma_f32_32x32x16_bf16 v[4:19], v[156:159], v[208:211], v[4:19]
	s_nop 0
	ds_read_b64_tr_b16 v[148:149], v200 offset:57344
	ds_read_b64_tr_b16 v[150:151], v201 offset:59392
	ds_read_b64_tr_b16 v[152:153], v202 offset:57344
	ds_read_b64_tr_b16 v[154:155], v203 offset:59392
	ds_read_b64_tr_b16 v[156:157], v204 offset:57344
	ds_read_b64_tr_b16 v[158:159], v205 offset:59392
	ds_read_b64_tr_b16 v[160:161], v206 offset:57344
	ds_read_b64_tr_b16 v[162:163], v207 offset:59392
	s_nop 0
	s_waitcnt lgkmcnt(14)
	v_mfma_f32_32x32x16_bf16 v[52:67], v[220:223], v[216:219], v[52:67]
	s_waitcnt lgkmcnt(12)
	v_mfma_f32_32x32x16_bf16 v[36:51], v[224:227], v[216:219], v[36:51]
	s_waitcnt lgkmcnt(10)
	v_mfma_f32_32x32x16_bf16 v[20:35], v[228:231], v[216:219], v[20:35]
	s_waitcnt lgkmcnt(8)
	v_mfma_f32_32x32x16_bf16 v[4:19], v[232:235], v[216:219], v[4:19]
	s_nop 0
	ds_read_b64_tr_b16 v[208:209], v200 offset:61440
	ds_read_b64_tr_b16 v[210:211], v201 offset:63488
	ds_read_b64_tr_b16 v[200:201], v202 offset:61440
	ds_read_b64_tr_b16 v[202:203], v203 offset:63488
	ds_read_b64_tr_b16 v[216:217], v204 offset:61440
	ds_read_b64_tr_b16 v[218:219], v205 offset:63488
	ds_read_b64_tr_b16 v[204:205], v206 offset:61440
	ds_read_b64_tr_b16 v[206:207], v207 offset:63488
	s_nop 0
	s_waitcnt lgkmcnt(14)
	v_mfma_f32_32x32x16_bf16 v[52:67], v[148:151], v[212:215], v[52:67]
	s_waitcnt lgkmcnt(12)
	v_mfma_f32_32x32x16_bf16 v[36:51], v[152:155], v[212:215], v[36:51]
	s_waitcnt lgkmcnt(10)
	v_mfma_f32_32x32x16_bf16 v[20:35], v[156:159], v[212:215], v[20:35]
	s_waitcnt lgkmcnt(8)
	v_mfma_f32_32x32x16_bf16 v[4:19], v[160:163], v[212:215], v[4:19]
	s_nop 0
	s_nop 0
	s_waitcnt lgkmcnt(6)
	v_mfma_f32_32x32x16_bf16 v[52:67], v[208:211], v[236:239], v[52:67]
	s_waitcnt lgkmcnt(4)
	v_mfma_f32_32x32x16_bf16 v[36:51], v[200:203], v[236:239], v[36:51]
	s_waitcnt lgkmcnt(2)
	v_mfma_f32_32x32x16_bf16 v[20:35], v[216:219], v[236:239], v[20:35]
	s_waitcnt lgkmcnt(0)
	v_mfma_f32_32x32x16_bf16 v[4:19], v[204:207], v[236:239], v[4:19]
	s_nop 0

; __device__ __forceinline__ unsigned cvtpk(float lo, float hi) { typedef __bf16 b2 __attribute__((ext_vector_type(2))); f32x2 v = {lo, hi}; b2 b = __builtin_convertvector(v, b2); return __builtin_bit_cast(unsigned, b); }
; __device__ __forceinline__ int crow(int r, int hi) { return (r & 3) + 8 * (r >> 2) + 4 * hi; }
; #define ATT_VREAD(dst, q_) do { const LAS char* vp_ = (const LAS char*)vb + (((q_) >> 1) * 32 + 16 * ((q_) & 1)) * VSTR; \
;         _Pragma("unroll") for (int d_ = 0; d_ < 4; ++d_) { dst[d_][0] = vtr(vp_ + voff[d_][0]); dst[d_][1] = vtr(vp_ + 8 * VSTR + voff[d_][1]); } } while (0)
;     ...
;         for (int r = 0; r < 16; ++r) { float p0 = __builtin_amdgcn_exp2f(s0[r] - mrun), p1 = __builtin_amdgcn_exp2f(s1[r] - mrun);
;             if (LAYER == 1) { const int kv = crow(r, hi); p0 = ((w0 >> kv) & 1u) ? p0 : 0.f; p1 = ((w1 >> kv) & 1u) ? p1 : 0.f; }
;             s0[r] = p0; s1[r] = p1; rsa[r & 3] += p0 + p1; }
;         lrun += (rsa[0] + rsa[1]) + (rsa[2] + rsa[3]);
; #pragma unroll
;         for (int s = 0; s < 2; ++s) {
;             v4u x; x.x = cvtpk(s0[8 * s + 0], s0[8 * s + 1]); x.y = cvtpk(s0[8 * s + 2], s0[8 * s + 3]); x.z = cvtpk(s0[8 * s + 4], s0[8 * s + 5]); x.w = cvtpk(s0[8 * s + 6], s0[8 * s + 7]); pb[0][s] = __builtin_bit_cast(bf16x8, x);
;             v4u y; y.x = cvtpk(s1[8 * s + 0], s1[8 * s + 1]); y.y = cvtpk(s1[8 * s + 2], s1[8 * s + 3]); y.z = cvtpk(s1[8 * s + 4], s1[8 * s + 5]); y.w = cvtpk(s1[8 * s + 6], s1[8 * s + 7]); pb[1][s] = __builtin_bit_cast(bf16x8, y); }
;     ...
;             if (wka) { vb = sa + KBUF + vlane; ATT_VREAD(vpre, 0); SM(wa0, wa1, a0, a1, pba);
;                 ATT_VREAD(va, 1); __builtin_amdgcn_s_setprio(1); ATT_PV(vpre, pba, 0); __builtin_amdgcn_s_setprio(0);
;                 ATT_VREAD(vbb, 2); __builtin_amdgcn_s_setprio(1); ATT_PV(va, pba, 1); __builtin_amdgcn_s_setprio(0);
;                 ATT_VREAD(va, 3); __builtin_amdgcn_s_setprio(1); ATT_PV(vbb, pba, 2); __builtin_amdgcn_s_setprio(0);
;                 __builtin_amdgcn_s_setprio(1); ATT_PV(va, pba, 3); __builtin_amdgcn_s_setprio(0); }
.LBB0_3323:
	v_sub_f32_e32 v66, v66, v170
	v_sub_f32_e32 v98, v98, v170
	v_sub_f32_e32 v68, v68, v170
	v_sub_f32_e32 v100, v100, v170
	v_exp_f32_e32 v66, v66
	v_exp_f32_e32 v98, v98
	v_sub_f32_e32 v67, v67, v170
	v_sub_f32_e32 v99, v99, v170
	v_exp_f32_e32 v68, v68
	v_exp_f32_e32 v100, v100
	v_sub_f32_e32 v69, v69, v170
	v_sub_f32_e32 v101, v101, v170
	v_exp_f32_e32 v67, v67
	v_exp_f32_e32 v99, v99
	v_exp_f32_e32 v69, v69
	v_exp_f32_e32 v101, v101
	v_sub_f32_e32 v70, v70, v170
	v_sub_f32_e32 v102, v102, v170
	v_sub_f32_e32 v72, v72, v170
	v_sub_f32_e32 v104, v104, v170
	v_exp_f32_e32 v70, v70
	v_exp_f32_e32 v102, v102
	v_exp_f32_e32 v72, v72
	v_exp_f32_e32 v104, v104
	v_sub_f32_e32 v71, v71, v170
	v_sub_f32_e32 v103, v103, v170
	v_sub_f32_e32 v73, v73, v170
	v_sub_f32_e32 v105, v105, v170
	v_exp_f32_e32 v71, v71
	v_exp_f32_e32 v103, v103
	v_exp_f32_e32 v73, v73
	v_exp_f32_e32 v105, v105
	v_sub_f32_e32 v74, v74, v170
	v_sub_f32_e32 v106, v106, v170
	v_sub_f32_e32 v76, v76, v170
	v_sub_f32_e32 v108, v108, v170
	v_exp_f32_e32 v74, v74
	v_exp_f32_e32 v106, v106
	v_exp_f32_e32 v76, v76
	v_exp_f32_e32 v108, v108
	v_sub_f32_e32 v75, v75, v170
	v_sub_f32_e32 v107, v107, v170
	v_sub_f32_e32 v77, v77, v170
	v_sub_f32_e32 v109, v109, v170
	v_exp_f32_e32 v75, v75
	v_exp_f32_e32 v107, v107
	v_exp_f32_e32 v77, v77
	v_exp_f32_e32 v109, v109
	v_sub_f32_e32 v78, v78, v170
	v_sub_f32_e32 v110, v110, v170
	v_sub_f32_e32 v80, v80, v170
	v_sub_f32_e32 v112, v112, v170
	ds_read_b64_tr_b16 v[222:223], v201 offset:20480
	ds_read_b64_tr_b16 v[224:225], v202 offset:22528
	ds_read_b64_tr_b16 v[226:227], v203 offset:20480
	ds_read_b64_tr_b16 v[228:229], v204 offset:22528
	ds_read_b64_tr_b16 v[230:231], v205 offset:20480
	ds_read_b64_tr_b16 v[232:233], v206 offset:22528
	ds_read_b64_tr_b16 v[234:235], v207 offset:20480
	ds_read_b64_tr_b16 v[236:237], v208 offset:22528
	v_exp_f32_e32 v78, v78
	v_exp_f32_e32 v110, v110
	v_exp_f32_e32 v80, v80
	v_exp_f32_e32 v112, v112
	v_sub_f32_e32 v79, v79, v170
	v_sub_f32_e32 v111, v111, v170
	v_sub_f32_e32 v81, v81, v170
	v_sub_f32_e32 v113, v113, v170
	v_exp_f32_e32 v79, v79
	v_exp_f32_e32 v111, v111
	v_exp_f32_e32 v81, v81
	v_exp_f32_e32 v113, v113
	s_nop 0
	v_add_f32_e32 v210, v66, v74
	v_add_f32_e32 v211, v67, v75
	v_add_f32_e32 v212, v68, v76
	v_add_f32_e32 v213, v69, v77
	v_add_f32_e32 v214, v70, v78
	v_add_f32_e32 v215, v71, v79
	v_add_f32_e32 v216, v72, v80
	v_add_f32_e32 v217, v73, v81
	v_add_f32_e32 v210, v210, v98
	v_add_f32_e32 v211, v211, v99
	v_add_f32_e32 v212, v212, v100
	v_add_f32_e32 v213, v213, v101
	v_add_f32_e32 v214, v214, v102
	v_add_f32_e32 v215, v215, v103
	v_add_f32_e32 v216, v216, v104
	v_add_f32_e32 v217, v217, v105
	v_add_f32_e32 v210, v210, v106
	v_add_f32_e32 v211, v211, v107
	v_add_f32_e32 v212, v212, v108
	v_add_f32_e32 v213, v213, v109
	v_add_f32_e32 v214, v214, v110
	v_add_f32_e32 v215, v215, v111
	v_add_f32_e32 v216, v216, v112
	v_add_f32_e32 v217, v217, v113
	v_add_f32_e32 v210, v210, v214
	v_add_f32_e32 v211, v211, v215
	v_add_f32_e32 v212, v212, v216
	v_add_f32_e32 v213, v213, v217
	v_add_f32_e32 v210, v210, v212
	v_add_f32_e32 v211, v211, v213
	v_add_f32_e32 v209, v210, v211
	v_cvt_pk_bf16_f32 v216, v102, v103
	v_cvt_pk_bf16_f32 v214, v98, v99
	v_cvt_pk_bf16_f32 v212, v70, v71
	v_cvt_pk_bf16_f32 v210, v66, v67
	v_cvt_pk_bf16_f32 v211, v68, v69
	v_cvt_pk_bf16_f32 v213, v72, v73
	v_cvt_pk_bf16_f32 v215, v100, v101
	v_cvt_pk_bf16_f32 v217, v104, v105
	v_cvt_pk_bf16_f32 v218, v74, v75
	v_cvt_pk_bf16_f32 v219, v76, v77
	v_cvt_pk_bf16_f32 v220, v78, v79
	v_cvt_pk_bf16_f32 v221, v80, v81
	v_cvt_pk_bf16_f32 v238, v106, v107
	v_cvt_pk_bf16_f32 v239, v108, v109
	v_cvt_pk_bf16_f32 v240, v110, v111
	v_cvt_pk_bf16_f32 v241, v112, v113
	s_nop 0
	s_waitcnt lgkmcnt(8)
	v_mfma_f32_32x32x16_bf16 v[50:65], v[150:153], v[210:213], v[50:65]
	v_add_f32_e32 v167, v167, v209
	v_mfma_f32_32x32x16_bf16 v[34:49], v[146:149], v[210:213], v[34:49]
	v_mfma_f32_32x32x16_bf16 v[18:33], v[158:161], v[210:213], v[18:33]
	v_mfma_f32_32x32x16_bf16 v[2:17], v[154:157], v[210:213], v[2:17]
	s_nop 0
	ds_read_b64_tr_b16 v[146:147], v201 offset:24576
	ds_read_b64_tr_b16 v[148:149], v202 offset:26624
	ds_read_b64_tr_b16 v[150:151], v203 offset:24576
	ds_read_b64_tr_b16 v[152:153], v204 offset:26624
	ds_read_b64_tr_b16 v[154:155], v205 offset:24576
	ds_read_b64_tr_b16 v[156:157], v206 offset:26624
	ds_read_b64_tr_b16 v[158:159], v207 offset:24576
	ds_read_b64_tr_b16 v[160:161], v208 offset:26624
	s_nop 0
	s_waitcnt lgkmcnt(14)
	v_mfma_f32_32x32x16_bf16 v[50:65], v[222:225], v[218:221], v[50:65]
	s_waitcnt lgkmcnt(12)
	v_mfma_f32_32x32x16_bf16 v[34:49], v[226:229], v[218:221], v[34:49]
	s_waitcnt lgkmcnt(10)
	v_mfma_f32_32x32x16_bf16 v[18:33], v[230:233], v[218:221], v[18:33]
	s_waitcnt lgkmcnt(8)
	v_mfma_f32_32x32x16_bf16 v[2:17], v[234:237], v[218:221], v[2:17]
	s_nop 0
	ds_read_b64_tr_b16 v[210:211], v201 offset:28672
	ds_read_b64_tr_b16 v[212:213], v202 offset:30720
	ds_read_b64_tr_b16 v[218:219], v203 offset:28672
	ds_read_b64_tr_b16 v[220:221], v204 offset:30720
	ds_read_b64_tr_b16 v[222:223], v205 offset:28672
	ds_read_b64_tr_b16 v[224:225], v206 offset:30720
	ds_read_b64_tr_b16 v[226:227], v207 offset:28672
	ds_read_b64_tr_b16 v[228:229], v208 offset:30720
	s_nop 0
	s_waitcnt lgkmcnt(14)
	v_mfma_f32_32x32x16_bf16 v[50:65], v[146:149], v[214:217], v[50:65]
	s_waitcnt lgkmcnt(12)
	v_mfma_f32_32x32x16_bf16 v[34:49], v[150:153], v[214:217], v[34:49]
	s_waitcnt lgkmcnt(10)
	v_mfma_f32_32x32x16_bf16 v[18:33], v[154:157], v[214:217], v[18:33]
	s_waitcnt lgkmcnt(8)
	v_mfma_f32_32x32x16_bf16 v[2:17], v[158:161], v[214:217], v[2:17]
	s_nop 0
	s_nop 0
	s_waitcnt lgkmcnt(6)
	v_mfma_f32_32x32x16_bf16 v[50:65], v[210:213], v[238:241], v[50:65]
	s_waitcnt lgkmcnt(4)
	v_mfma_f32_32x32x16_bf16 v[34:49], v[218:221], v[238:241], v[34:49]
	s_waitcnt lgkmcnt(2)
	v_mfma_f32_32x32x16_bf16 v[18:33], v[222:225], v[238:241], v[18:33]
	s_waitcnt lgkmcnt(0)
	v_mfma_f32_32x32x16_bf16 v[2:17], v[226:229], v[238:241], v[2:17]
	s_nop 0

; __device__ __forceinline__ unsigned cvtpk(float lo, float hi) { typedef __bf16 b2 __attribute__((ext_vector_type(2))); f32x2 v = {lo, hi}; b2 b = __builtin_convertvector(v, b2); return __builtin_bit_cast(unsigned, b); }
; __device__ __forceinline__ int crow(int r, int hi) { return (r & 3) + 8 * (r >> 2) + 4 * hi; }
; #define ATT_VREAD(dst, q_) do { const LAS char* vp_ = (const LAS char*)vb + (((q_) >> 1) * 32 + 16 * ((q_) & 1)) * VSTR; \
;         _Pragma("unroll") for (int d_ = 0; d_ < 4; ++d_) { dst[d_][0] = vtr(vp_ + voff[d_][0]); dst[d_][1] = vtr(vp_ + 8 * VSTR + voff[d_][1]); } } while (0)
;     ...
;         for (int r = 0; r < 16; ++r) { float p0 = __builtin_amdgcn_exp2f(s0[r] - mrun), p1 = __builtin_amdgcn_exp2f(s1[r] - mrun);
;             if (LAYER == 1) { const int kv = crow(r, hi); p0 = ((w0 >> kv) & 1u) ? p0 : 0.f; p1 = ((w1 >> kv) & 1u) ? p1 : 0.f; }
;             s0[r] = p0; s1[r] = p1; rsa[r & 3] += p0 + p1; }
;         lrun += (rsa[0] + rsa[1]) + (rsa[2] + rsa[3]);
; #pragma unroll
;         for (int s = 0; s < 2; ++s) {
;             v4u x; x.x = cvtpk(s0[8 * s + 0], s0[8 * s + 1]); x.y = cvtpk(s0[8 * s + 2], s0[8 * s + 3]); x.z = cvtpk(s0[8 * s + 4], s0[8 * s + 5]); x.w = cvtpk(s0[8 * s + 6], s0[8 * s + 7]); pb[0][s] = __builtin_bit_cast(bf16x8, x);
;             v4u y; y.x = cvtpk(s1[8 * s + 0], s1[8 * s + 1]); y.y = cvtpk(s1[8 * s + 2], s1[8 * s + 3]); y.z = cvtpk(s1[8 * s + 4], s1[8 * s + 5]); y.w = cvtpk(s1[8 * s + 6], s1[8 * s + 7]); pb[1][s] = __builtin_bit_cast(bf16x8, y); }
;     ...
;             if (wkb) { vb = sbb + KBUF + vlane; ATT_VREAD(vpre, 0); SM(wb0, wb1, b0, b1, pbb);
;                 ATT_VREAD(va, 1); __builtin_amdgcn_s_setprio(1); ATT_PV(vpre, pbb, 0); __builtin_amdgcn_s_setprio(0);
;                 ATT_VREAD(vbb, 2); __builtin_amdgcn_s_setprio(1); ATT_PV(va, pbb, 1); __builtin_amdgcn_s_setprio(0);
;                 ATT_VREAD(va, 3); __builtin_amdgcn_s_setprio(1); ATT_PV(vbb, pbb, 2); __builtin_amdgcn_s_setprio(0);
;                 __builtin_amdgcn_s_setprio(1); ATT_PV(va, pbb, 3); __builtin_amdgcn_s_setprio(0); }
.LBB0_3327:
	v_sub_f32_e32 v82, v82, v170
	v_sub_f32_e32 v114, v114, v170
	v_sub_f32_e32 v84, v84, v170
	v_sub_f32_e32 v116, v116, v170
	v_exp_f32_e32 v82, v82
	v_exp_f32_e32 v114, v114
	v_sub_f32_e32 v83, v83, v170
	v_sub_f32_e32 v115, v115, v170
	v_exp_f32_e32 v84, v84
	v_exp_f32_e32 v116, v116
	v_sub_f32_e32 v85, v85, v170
	v_sub_f32_e32 v117, v117, v170
	v_exp_f32_e32 v83, v83
	v_exp_f32_e32 v115, v115
	v_exp_f32_e32 v85, v85
	v_exp_f32_e32 v117, v117
	v_sub_f32_e32 v86, v86, v170
	v_sub_f32_e32 v118, v118, v170
	v_sub_f32_e32 v88, v88, v170
	v_sub_f32_e32 v120, v120, v170
	v_exp_f32_e32 v86, v86
	v_exp_f32_e32 v118, v118
	v_exp_f32_e32 v88, v88
	v_exp_f32_e32 v120, v120
	v_sub_f32_e32 v87, v87, v170
	v_sub_f32_e32 v119, v119, v170
	v_sub_f32_e32 v89, v89, v170
	v_sub_f32_e32 v121, v121, v170
	v_exp_f32_e32 v87, v87
	v_exp_f32_e32 v119, v119
	v_exp_f32_e32 v89, v89
	v_exp_f32_e32 v121, v121
	v_sub_f32_e32 v90, v90, v170
	v_sub_f32_e32 v122, v122, v170
	v_sub_f32_e32 v92, v92, v170
	v_sub_f32_e32 v124, v124, v170
	v_exp_f32_e32 v90, v90
	v_exp_f32_e32 v122, v122
	v_exp_f32_e32 v92, v92
	v_exp_f32_e32 v124, v124
	v_sub_f32_e32 v91, v91, v170
	v_sub_f32_e32 v123, v123, v170
	v_sub_f32_e32 v93, v93, v170
	v_sub_f32_e32 v125, v125, v170
	v_exp_f32_e32 v91, v91
	v_exp_f32_e32 v123, v123
	v_exp_f32_e32 v93, v93
	v_exp_f32_e32 v125, v125
	v_sub_f32_e32 v94, v94, v170
	v_sub_f32_e32 v126, v126, v170
	v_sub_f32_e32 v96, v96, v170
	v_sub_f32_e32 v128, v128, v170
	ds_read_b64_tr_b16 v[222:223], v201 offset:53248
	ds_read_b64_tr_b16 v[224:225], v202 offset:55296
	ds_read_b64_tr_b16 v[226:227], v203 offset:53248
	ds_read_b64_tr_b16 v[228:229], v204 offset:55296
	ds_read_b64_tr_b16 v[230:231], v205 offset:53248
	ds_read_b64_tr_b16 v[232:233], v206 offset:55296
	ds_read_b64_tr_b16 v[234:235], v207 offset:53248
	ds_read_b64_tr_b16 v[236:237], v208 offset:55296
	v_exp_f32_e32 v94, v94
	v_exp_f32_e32 v126, v126
	v_exp_f32_e32 v96, v96
	v_exp_f32_e32 v128, v128
	v_sub_f32_e32 v95, v95, v170
	v_sub_f32_e32 v127, v127, v170
	v_sub_f32_e32 v97, v97, v170
	v_sub_f32_e32 v129, v129, v170
	v_exp_f32_e32 v95, v95
	v_exp_f32_e32 v127, v127
	v_exp_f32_e32 v97, v97
	v_exp_f32_e32 v129, v129
	s_nop 0
	v_add_f32_e32 v210, v82, v90
	v_add_f32_e32 v211, v83, v91
	v_add_f32_e32 v212, v84, v92
	v_add_f32_e32 v213, v85, v93
	v_add_f32_e32 v214, v86, v94
	v_add_f32_e32 v215, v87, v95
	v_add_f32_e32 v216, v88, v96
	v_add_f32_e32 v217, v89, v97
	v_add_f32_e32 v210, v210, v114
	v_add_f32_e32 v211, v211, v115
	v_add_f32_e32 v212, v212, v116
	v_add_f32_e32 v213, v213, v117
	v_add_f32_e32 v214, v214, v118
	v_add_f32_e32 v215, v215, v119
	v_add_f32_e32 v216, v216, v120
	v_add_f32_e32 v217, v217, v121
	v_add_f32_e32 v210, v210, v122
	v_add_f32_e32 v211, v211, v123
	v_add_f32_e32 v212, v212, v124
	v_add_f32_e32 v213, v213, v125
	v_add_f32_e32 v214, v214, v126
	v_add_f32_e32 v215, v215, v127
	v_add_f32_e32 v216, v216, v128
	v_add_f32_e32 v217, v217, v129
	v_add_f32_e32 v210, v210, v214
	v_add_f32_e32 v211, v211, v215
	v_add_f32_e32 v212, v212, v216
	v_add_f32_e32 v213, v213, v217
	v_add_f32_e32 v210, v210, v212
	v_add_f32_e32 v211, v211, v213
	v_add_f32_e32 v209, v210, v211
	v_cvt_pk_bf16_f32 v216, v118, v119
	v_cvt_pk_bf16_f32 v214, v114, v115
	v_cvt_pk_bf16_f32 v212, v86, v87
	v_cvt_pk_bf16_f32 v210, v82, v83
	v_cvt_pk_bf16_f32 v211, v84, v85
	v_cvt_pk_bf16_f32 v213, v88, v89
	v_cvt_pk_bf16_f32 v215, v116, v117
	v_cvt_pk_bf16_f32 v217, v120, v121
	v_cvt_pk_bf16_f32 v218, v90, v91
	v_cvt_pk_bf16_f32 v219, v92, v93
	v_cvt_pk_bf16_f32 v220, v94, v95
	v_cvt_pk_bf16_f32 v221, v96, v97
	v_cvt_pk_bf16_f32 v238, v122, v123
	v_cvt_pk_bf16_f32 v239, v124, v125
	v_cvt_pk_bf16_f32 v240, v126, v127
	v_cvt_pk_bf16_f32 v241, v128, v129
	s_nop 0
	s_waitcnt lgkmcnt(8)
	v_mfma_f32_32x32x16_bf16 v[50:65], v[150:153], v[210:213], v[50:65]
	v_add_f32_e32 v167, v167, v209
	v_mfma_f32_32x32x16_bf16 v[34:49], v[146:149], v[210:213], v[34:49]
	v_mfma_f32_32x32x16_bf16 v[18:33], v[158:161], v[210:213], v[18:33]
	v_mfma_f32_32x32x16_bf16 v[2:17], v[154:157], v[210:213], v[2:17]
	s_nop 0
	ds_read_b64_tr_b16 v[146:147], v201 offset:57344
	ds_read_b64_tr_b16 v[148:149], v202 offset:59392
	ds_read_b64_tr_b16 v[150:151], v203 offset:57344
	ds_read_b64_tr_b16 v[152:153], v204 offset:59392
	ds_read_b64_tr_b16 v[154:155], v205 offset:57344
	ds_read_b64_tr_b16 v[156:157], v206 offset:59392
	ds_read_b64_tr_b16 v[158:159], v207 offset:57344
	ds_read_b64_tr_b16 v[160:161], v208 offset:59392
	s_nop 0
	s_waitcnt lgkmcnt(14)
	v_mfma_f32_32x32x16_bf16 v[50:65], v[222:225], v[218:221], v[50:65]
	s_waitcnt lgkmcnt(12)
	v_mfma_f32_32x32x16_bf16 v[34:49], v[226:229], v[218:221], v[34:49]
	s_waitcnt lgkmcnt(10)
	v_mfma_f32_32x32x16_bf16 v[18:33], v[230:233], v[218:221], v[18:33]
	s_waitcnt lgkmcnt(8)
	v_mfma_f32_32x32x16_bf16 v[2:17], v[234:237], v[218:221], v[2:17]
	s_nop 0
	ds_read_b64_tr_b16 v[210:211], v201 offset:61440
	ds_read_b64_tr_b16 v[212:213], v202 offset:63488
	ds_read_b64_tr_b16 v[218:219], v203 offset:61440
	ds_read_b64_tr_b16 v[220:221], v204 offset:63488
	ds_read_b64_tr_b16 v[202:203], v205 offset:61440
	ds_read_b64_tr_b16 v[204:205], v206 offset:63488
	ds_read_b64_tr_b16 v[206:207], v207 offset:61440
	ds_read_b64_tr_b16 v[208:209], v208 offset:63488
	s_nop 0
	s_waitcnt lgkmcnt(14)
	v_mfma_f32_32x32x16_bf16 v[50:65], v[146:149], v[214:217], v[50:65]
	s_waitcnt lgkmcnt(12)
	v_mfma_f32_32x32x16_bf16 v[34:49], v[150:153], v[214:217], v[34:49]
	s_waitcnt lgkmcnt(10)
	v_mfma_f32_32x32x16_bf16 v[18:33], v[154:157], v[214:217], v[18:33]
	s_waitcnt lgkmcnt(8)
	v_mfma_f32_32x32x16_bf16 v[2:17], v[158:161], v[214:217], v[2:17]
	s_nop 0
	s_nop 0
	s_waitcnt lgkmcnt(6)
	v_mfma_f32_32x32x16_bf16 v[50:65], v[210:213], v[238:241], v[50:65]
	s_waitcnt lgkmcnt(4)
	v_mfma_f32_32x32x16_bf16 v[34:49], v[218:221], v[238:241], v[34:49]
	s_waitcnt lgkmcnt(2)
	v_mfma_f32_32x32x16_bf16 v[18:33], v[202:205], v[238:241], v[18:33]
	s_waitcnt lgkmcnt(0)
	v_mfma_f32_32x32x16_bf16 v[2:17], v[206:209], v[238:241], v[2:17]
	s_nop 0
